# E34: sample-FoX: prefetch distance 2 tiles (E32, landing set in v192-195/v246-253/v146-149) combined with LDS-read pipelining of the single computing wave (E33); on E30
# speedup vs baseline: 1.0084x; 1.0084x over previous
.LBB0_1452:
	s_or_b64 exec, exec, s[18:19]
	v_mul_lo_u32 v131, v4, s72
	v_lshlrev_b32_e32 v132, 4, v6
	v_add3_u32 v6, 0, v131, v132
	v_lshrrev_b32_e32 v2, 2, v2
	s_cmp_lt_i32 s90, s12
	v_cvt_pk_bf16_f32 v54, v102, v103
	v_cvt_pk_bf16_f32 v55, v104, v105
	v_cvt_pk_bf16_f32 v56, v98, v99
	v_cvt_pk_bf16_f32 v57, v100, v101
	v_mad_u64_u32 v[8:9], s[10:11], v4, 48, v[6:7]
	v_and_or_b32 v5, v2, 3, v216
	v_and_or_b32 v2, v2, 4, v225
	v_mov_b32_e32 v16, v3
	v_mov_b32_e32 v17, v3
	s_cselect_b64 s[78:79], -1, 0
	s_add_i32 s6, s90, s8
	s_add_i32 s8, s9, 63
	s_waitcnt lgkmcnt(0)
	s_barrier
	s_barrier
	v_cvt_pk_bf16_f32 v50, v110, v111
	v_cvt_pk_bf16_f32 v51, v112, v113
	v_cvt_pk_bf16_f32 v52, v106, v107
	v_cvt_pk_bf16_f32 v53, v108, v109
	v_mul_lo_u32 v133, v4, s73
	ds_write_b128 v6, v[54:57]
	ds_write_b128 v8, v[50:53] offset:9216
	v_lshlrev_b32_e32 v123, 3, v2
	v_mul_u32_u24_e32 v130, 0xc0, v5
	v_add_u32_e32 v135, 64, v4
	s_lshl_b32 s10, s7, 6
	v_mov_b32_e32 v2, v3
	v_mov_b32_e32 v4, v3
	v_mov_b32_e32 v5, v3
	v_mov_b32_e32 v6, v3
	v_mov_b32_e32 v7, v3
	v_mov_b32_e32 v8, v3
	v_mov_b32_e32 v9, v3
	v_mov_b32_e32 v10, v3
	v_mov_b32_e32 v11, v3
	v_mov_b32_e32 v12, v3
	v_mov_b32_e32 v13, v3
	v_mov_b32_e32 v14, v3
	v_mov_b32_e32 v15, v3
	v_mov_b64_e32 v[32:33], v[16:17]
	v_mov_b64_e32 v[48:49], v[16:17]
	s_lshr_b32 s8, s8, 6
	s_add_i32 s9, s6, 31
	v_add_u32_e32 v134, s6, v188
	v_subrev_u32_e32 v136, s10, v135
	s_mov_b32 s10, 0
	v_mov_b32_e32 v122, 0xf149f2ca
	v_mov_b32_e32 v119, 0
	s_mov_b32 s11, 1
	v_mov_b32_e32 v137, v187
	v_mov_b64_e32 v[30:31], v[14:15]
	v_mov_b64_e32 v[28:29], v[12:13]
	v_mov_b64_e32 v[26:27], v[10:11]
	v_mov_b64_e32 v[24:25], v[8:9]
	v_mov_b64_e32 v[22:23], v[6:7]
	v_mov_b64_e32 v[20:21], v[4:5]
	v_mov_b64_e32 v[18:19], v[2:3]
	v_mov_b64_e32 v[46:47], v[14:15]
	v_mov_b64_e32 v[44:45], v[12:13]
	v_mov_b64_e32 v[42:43], v[10:11]
	v_mov_b64_e32 v[40:41], v[8:9]
	v_mov_b64_e32 v[38:39], v[6:7]
	v_mov_b64_e32 v[36:37], v[4:5]
	v_mov_b64_e32 v[34:35], v[2:3]
	s_waitcnt lgkmcnt(0)
	s_barrier
	s_cmp_gt_u32 s7, 1
	s_cbranch_scc0 .Lsmp_nopre
	v_add_u32_e32 v4, s10, v135
	v_ashrrev_i32_e32 v5, 31, v4
	v_lshlrev_b64 v[4:5], 9, v[4:5]
	v_lshl_add_u64 v[4:5], v[4:5], 0, v[120:121]
	v_lshlrev_b64 v[4:5], 2, v[4:5]
	v_lshl_add_u64 v[6:7], s[68:69], 0, v[4:5]
	v_lshl_add_u64 v[4:5], s[76:77], 0, v[4:5]
	global_load_dwordx4 v[192:195], v[6:7], off offset:16 nt
	global_load_dwordx4 v[246:249], v[6:7], off nt
	global_load_dwordx4 v[250:253], v[4:5], off offset:16 nt
	global_load_dwordx4 v[146:149], v[4:5], off nt

.Lsmp_loadB:
	global_load_dwordx4 v[192:195], v[6:7], off offset:16 nt
	global_load_dwordx4 v[246:249], v[6:7], off nt
	global_load_dwordx4 v[250:253], v[4:5], off offset:16 nt
	global_load_dwordx4 v[146:149], v[4:5], off nt

.Lsmp_cvtB:
	v_cvt_pk_bf16_f32 v12, v246, v247
	v_cvt_pk_bf16_f32 v13, v248, v249
	v_cvt_pk_bf16_f32 v14, v192, v193
	v_cvt_pk_bf16_f32 v15, v194, v195
	v_cvt_pk_bf16_f32 v114, v146, v147
	v_cvt_pk_bf16_f32 v115, v148, v149
	v_cvt_pk_bf16_f32 v116, v250, v251
	v_cvt_pk_bf16_f32 v117, v252, v253

	.amdhsa_kernel _Z8yoco_fwd6Params
		.amdhsa_group_segment_fixed_size 0
		.amdhsa_private_segment_fixed_size 0
		.amdhsa_kernarg_size 472
		.amdhsa_user_sgpr_count 2
		.amdhsa_user_sgpr_dispatch_ptr 0
		.amdhsa_user_sgpr_queue_ptr 0
		.amdhsa_user_sgpr_kernarg_segment_ptr 1
		.amdhsa_user_sgpr_dispatch_id 0
		.amdhsa_user_sgpr_kernarg_preload_length 0
		.amdhsa_user_sgpr_kernarg_preload_offset 0
		.amdhsa_user_sgpr_private_segment_size 0
		.amdhsa_uses_dynamic_stack 0
		.amdhsa_enable_private_segment 0
		.amdhsa_system_sgpr_workgroup_id_x 1
		.amdhsa_system_sgpr_workgroup_id_y 0
		.amdhsa_system_sgpr_workgroup_id_z 0
		.amdhsa_system_sgpr_workgroup_info 0
		.amdhsa_system_vgpr_workitem_id 2
		.amdhsa_next_free_vgpr 254
		.amdhsa_next_free_sgpr 102
		.amdhsa_accum_offset 256
		.amdhsa_reserve_vcc 1
		.amdhsa_float_round_mode_32 0
		.amdhsa_float_round_mode_16_64 0
		.amdhsa_float_denorm_mode_32 3
		.amdhsa_float_denorm_mode_16_64 3
		.amdhsa_dx10_clamp 1
		.amdhsa_ieee_mode 1
		.amdhsa_fp16_overflow 0
		.amdhsa_tg_split 0
		.amdhsa_exception_fp_ieee_invalid_op 0
		.amdhsa_exception_fp_denorm_src 0
		.amdhsa_exception_fp_ieee_div_zero 0
		.amdhsa_exception_fp_ieee_overflow 0
		.amdhsa_exception_fp_ieee_underflow 0
		.amdhsa_exception_fp_ieee_inexact 0
		.amdhsa_exception_int_div_zero 0
	.end_amdhsa_kernel

amdhsa.kernels:
  - .agpr_count:     0
    .args:
      - .offset:         0
        .size:           216
        .value_kind:     by_value
      - .offset:         216
        .size:           4
        .value_kind:     hidden_block_count_x
      - .offset:         220
        .size:           4
        .value_kind:     hidden_block_count_y
      - .offset:         224
        .size:           4
        .value_kind:     hidden_block_count_z
      - .offset:         228
        .size:           2
        .value_kind:     hidden_group_size_x
      - .offset:         230
        .size:           2
        .value_kind:     hidden_group_size_y
      - .offset:         232
        .size:           2
        .value_kind:     hidden_group_size_z
      - .offset:         234
        .size:           2
        .value_kind:     hidden_remainder_x
      - .offset:         236
        .size:           2
        .value_kind:     hidden_remainder_y
      - .offset:         238
        .size:           2
        .value_kind:     hidden_remainder_z
      - .offset:         256
        .size:           8
        .value_kind:     hidden_global_offset_x
      - .offset:         264
        .size:           8
        .value_kind:     hidden_global_offset_y
      - .offset:         272
        .size:           8
        .value_kind:     hidden_global_offset_z
      - .offset:         280
        .size:           2
        .value_kind:     hidden_grid_dims
      - .offset:         304
        .size:           8
        .value_kind:     hidden_multigrid_sync_arg
      - .offset:         336
        .size:           4
        .value_kind:     hidden_dynamic_lds_size
    .group_segment_fixed_size: 0
    .kernarg_segment_align: 8
    .kernarg_segment_size: 472
    .language:       OpenCL C
    .language_version:
      - 2
      - 0
    .max_flat_workgroup_size: 512
    .name:           _Z8yoco_fwd6Params
    .private_segment_fixed_size: 0
    .sgpr_count:     108
    .sgpr_spill_count: 56
    .symbol:         _Z8yoco_fwd6Params.kd
    .uniform_work_group_size: 1
    .uses_dynamic_stack: false
    .vgpr_count:     254
    .vgpr_spill_count: 0
    .wavefront_size: 64
